# v58 plus spatial-gating thread remap (wave = one channel quarter, lane = position) so the bf16 transposing LDS writes of the LayerNorm stage are bank-conflict free (was 4-way)
# speedup vs baseline: 1.0092x; 1.0092x over previous
; DI unsigned pk2(float lo, float hi) { f32x2 v = {lo, hi}; bf16v2 r = __builtin_convertvector(v, bf16v2); return __builtin_bit_cast(unsigned, r); }
; DI float bflo(unsigned w) { return __uint_as_float(w << 16); }
; DI float bfhi(unsigned w) { return __uint_as_float(w & 0xffff0000u); }
; DI void phase_spatial(LAS unsigned char* lds, const bf16_t* GV, bf16_t* UG, const f32x2* STATS, const float* ln_w, const float* ln_b, const float* w_s, const float* b_s, int G) {
;     ...
;     for (int it = blockIdx.x; it < 1024; it += G) {
;         const int g = it & 7, n = (it >> 3) & 31, b = it >> 8;
;         const size_t rowbase = (size_t)b * SEQ + (size_t)n * 128;
;         __syncthreads();
;         {
;             const int s = tid >> 2, cq = tid & 3; const f32x2 st = STATS[rowbase + s];
;             const bf16_t* p = GV + (rowbase + s) * D + 128 * g + 32 * cq;
; #pragma unroll
;             for (int q = 0; q < 4; ++q) { const u32x4 a = *(const u32x4*)(p + 8 * q); const unsigned aw[4] = {a.x, a.y, a.z, a.w};
;                 const f32x4 w0 = *(const f32x4*)(ln_w + 128 * g + 32 * cq + 8 * q), w1 = *(const f32x4*)(ln_w + 128 * g + 32 * cq + 8 * q + 4);
;                 const f32x4 c0 = *(const f32x4*)(ln_b + 128 * g + 32 * cq + 8 * q), c1 = *(const f32x4*)(ln_b + 128 * g + 32 * cq + 8 * q + 4);
;                 const float wv[8] = {w0.x, w0.y, w0.z, w0.w, w1.x, w1.y, w1.z, w1.w}, bv[8] = {c0.x, c0.y, c0.z, c0.w, c1.x, c1.y, c1.z, c1.w};
; #pragma unroll
;                 for (int w = 0; w < 4; ++w) { const float y0 = (bflo(aw[w]) - st.x) * st.y * wv[2 * w] + bv[2 * w], y1 = (bfhi(aw[w]) - st.x) * st.y * wv[2 * w + 1] + bv[2 * w + 1];
;                     const unsigned pk = pk2(y0, y1); const int cc = 32 * cq + 8 * q + 2 * w;
;                     VL[cc * 136 + s] = (bf16_t)(pk & 0xffffu); VL[(cc + 1) * 136 + s] = (bf16_t)(pk >> 16); } }
;             if (g != g_last) {
;                 const int t = tid >> 2, sq = tid & 3; const float* wp = w_s + ((size_t)g * 128 + t) * 128 + 32 * sq;
.LBB0_133:
	v_readlane_b32 s0, v243, 33
	v_mov_b32_e32 v0, v136
	v_readlane_b32 s1, v243, 34
	s_waitcnt vmcnt(0)
	s_barrier
	s_andn2_b64 vcc, exec, s[0:1]
	v_readfirstlane_b32 s2, v0
	s_cbranch_vccnz .LBB0_138
	v_readlane_b32 s0, v241, 50
	v_readlane_b32 s1, v241, 51
	s_mov_b32 s12, s0
	s_lshl_b32 s0, s0, 10
	s_ashr_i32 s1, s0, 31
	s_lshl_b64 s[6:7], s[0:1], 2
	s_add_u32 s0, s52, s6
	s_mov_b32 s10, s12
	s_addc_u32 s1, s53, s7
	s_ashr_i32 s13, s12, 31
	v_writelane_b32 v241, s10, 50
	v_lshrrev_b32_e32 v1, 2, v0
	v_and_b32_e32 v2, 0x60, v1
	v_writelane_b32 v241, s11, 51
	s_lshl_b64 s[10:11], s[12:13], 19
	v_readlane_b32 s12, v242, 34
	v_readlane_b32 s26, v242, 48
	v_readlane_b32 s27, v242, 49
	s_add_u32 s10, s26, s10
	v_readlane_b32 s24, v242, 46
	s_addc_u32 s11, s27, s11
	v_readlane_b32 s13, v242, 35
	v_readlane_b32 s25, v242, 47
	s_add_u32 s12, s24, s6
	v_readlane_b32 s22, v242, 44
	s_addc_u32 s13, s25, s7
	v_readlane_b32 s23, v242, 45
	s_add_u32 s6, s22, s6
	s_addc_u32 s7, s23, s7
	s_ashr_i32 s3, s2, 6
	v_lshlrev_b32_e32 v48, 2, v2
	v_and_b32_e32 v40, 0x7f, v0
	v_lshl_add_u64 v[42:43], s[6:7], 0, v[48:49]
	v_lshl_add_u64 v[46:47], s[10:11], 0, v[48:49]
	s_movk_i32 s10, 0x110
	s_lshl_b32 s6, s3, 5
	s_mulk_i32 s3, 0xa00
	v_and_b32_e32 v51, 31, v0
	v_mul_lo_u32 v1, v40, s10
	v_lshlrev_b32_e32 v3, 1, v2
	s_and_b32 s6, s6, 0x60
	s_add_i32 s3, s3, 0
	v_lshl_add_u64 v[44:45], s[12:13], 0, v[48:49]
	v_add3_u32 v56, 0, v1, v3
	v_or_b32_e32 v1, s6, v51
	s_add_i32 s3, s3, 0x11000
	s_lshl_b32 s6, s6, 1
	v_readlane_b32 s12, v241, 54
	v_readlane_b32 s13, v241, 55
	s_add_u32 s6, s12, s6
	v_lshrrev_b32_e32 v3, 2, v0
	v_bfe_u32 v50, v0, 2, 4
	s_addc_u32 s7, s13, 0
	v_lshlrev_b32_e32 v0, 4, v0
	s_ashr_i32 s2, s2, 2
	v_and_b32_e32 v48, 48, v0
	s_andn2_b32 s2, s2, 63
	v_and_b32_e32 v3, 8, v3
	v_lshl_add_u64 v[52:53], s[6:7], 0, v[48:49]
	v_mul_u32_u24_e32 v6, 0x110, v2
	v_lshlrev_b32_e32 v7, 1, v40
	s_or_b32 s6, s2, 32
	v_lshl_add_u32 v4, v3, 1, 0
	v_add_u32_e32 v0, s3, v48
	v_mov_b32_e32 v5, s3
	s_movk_i32 s3, 0x50
	v_add3_u32 v58, 0, v6, v7
	v_or_b32_e32 v6, s2, v51
	v_or_b32_e32 v7, s6, v51
	v_readlane_b32 s14, v242, 36
	v_readlane_b32 s15, v242, 37
	v_readlane_b32 s16, v242, 38
	v_readlane_b32 s20, v242, 42
	v_mad_u32_u24 v57, v1, s10, v4
	v_mul_u32_u24_e32 v1, 0x50, v50
	v_mad_u32_u24 v5, v51, s3, v5
	v_mul_lo_u32 v6, v6, s10
	v_mul_lo_u32 v7, v7, s10
	v_ashrrev_i32_e32 v41, 31, v40
	s_ashr_i32 s3, s2, 31
	s_ashr_i32 s7, s6, 31
	s_mov_b32 s16, -1
	v_lshlrev_b32_e32 v48, 1, v2
	v_add_u32_e32 v59, v4, v6
	v_add_u32_e32 v60, v0, v1
	v_add_u32_e32 v61, v5, v3
	v_add_u32_e32 v62, v4, v7
	v_readlane_b32 s14, v242, 51
	s_mov_b32 s15, s45
	v_readlane_b32 s20, v242, 52
	v_readlane_b32 s17, v242, 39
	v_readlane_b32 s18, v242, 40
	v_readlane_b32 s19, v242, 41
	v_readlane_b32 s21, v242, 43
	s_branch .LBB0_136
